# group-0 state row reads issued before the tile barrier (private table), K ladder after it
# baseline (speedup 1.0000x reference)
; #define LAS __attribute__((address_space(3)))
; #define MFMA16(a, b, c) __builtin_amdgcn_mfma_f32_16x16x32_bf16((a), (b), (c), 0, 0, 0)
; __device__ __forceinline__ void sel_group(const LAS bf16_t* Kt, const LAS bf16_t* Vt, LAS float* S, const bf16x8 qB0, const bf16x8 qB1, int jc, int rc, bool valid, bool masked, int tw64, int lr, int q) {
;     LAS float* Srow = S + (jc * 3 + rc) * 68;
;     const float mref = Srow[65]; const bool st = Srow[66] != 0.f;
;     f32x4 acc[4];
; #pragma unroll
;     for (int dt = 0; dt < 4; ++dt) acc[dt] = *(const LAS f32x4*)(Srow + 16 * dt + 4 * q);
;     float lc = Srow[64];
;     const float nm = valid ? -mref : -1e30f;
;     const f32x4 c0 = (f32x4){nm, nm, nm, nm};
;     const LAS bf16_t* kbase = Kt + lr * 72 + 8 * q;
;     f32x4 s[4];
;     {
;         bf16x8 kf[2][2];
;         kf[0][0] = *(const LAS bf16x8*)(kbase); kf[0][1] = *(const LAS bf16x8*)(kbase + 32);
; #pragma unroll
;         for (int mt = 0; mt < 4; ++mt) {
;             if (mt < 3) { kf[(mt + 1) & 1][0] = *(const LAS bf16x8*)(kbase + 16 * (mt + 1) * 72); kf[(mt + 1) & 1][1] = *(const LAS bf16x8*)(kbase + 16 * (mt + 1) * 72 + 32); }
;             __builtin_amdgcn_sched_barrier(0);
;             __builtin_amdgcn_s_setprio(1); s[mt] = MFMA16(kf[mt & 1][0], qB0, c0); s[mt] = MFMA16(kf[mt & 1][1], qB1, s[mt]); __builtin_amdgcn_s_setprio(0);
;             __builtin_amdgcn_sched_barrier(0);
;         }
;     }
;     if (masked) {
;         const int hq = tw64 + jc - 4 * q;
; #pragma unroll
;         for (int mt = 0; mt < 4; ++mt)
; #pragma unroll
;             for (int i = 0; i < 4; ++i) s[mt][i] = ((16 * mt + i) <= hq) ? s[mt][i] : -1e30f;
.Lsp_gdone_loop:
	s_cmp_eq_u32 s101, 1
	s_cselect_b64 s[2:3], -1, 0
	s_cmp_eq_u32 s45, s38
	s_cselect_b64 s[12:13], -1, 0
	v_add_u32_e32 v48, s6, v99
	v_add_u32_e32 v117, v48, v97
	v_cndmask_b32_e64 v48, 0, 1, s[12:13]
	v_add3_u32 v115, s6, v104, v114
	s_nop 0
	v_cmp_ne_u32_e64 s[72:73], 1, v48
	s_cmp_eq_u32 s10, 0
	s_cbranch_scc1 .Lsp_nostate
	v_mad_u64_u32 v[48:49], s[4:5], v120, 3, v[88:89]
	v_mul_lo_u32 v48, v48, s36
	v_add_u32_e32 v119, s49, v48
	v_add_u32_e32 v48, v119, v97
	ds_read_b96 v[84:86], v119 offset:46336
	ds_read_b128 v[60:63], v48 offset:46080
	ds_read_b128 v[56:59], v48 offset:46144
	ds_read_b128 v[52:55], v48 offset:46208
	ds_read_b128 v[48:51], v48 offset:46272
	s_waitcnt lgkmcnt(5)
	s_barrier
	s_branch .Lsp_g0
.Lsp_nostate:
	s_waitcnt lgkmcnt(0)
	s_barrier
	s_branch .LBB0_1078
.Lsp_g0:
	ds_read_b128 v[64:67], v117
	ds_read_b128 v[68:71], v117 offset:64
	ds_read_b128 v[72:75], v117 offset:2304
	ds_read_b128 v[122:125], v117 offset:2368
	ds_read_b128 v[130:133], v117 offset:4608
	ds_read_b128 v[134:137], v117 offset:4672
	ds_read_b128 v[174:177], v117 offset:6912
	ds_read_b128 v[138:141], v117 offset:6976
	s_waitcnt lgkmcnt(12)
	v_cndmask_b32_e64 v126, v222, -v85, s[76:77]
	v_mov_b32_e32 v127, v126
	v_mov_b32_e32 v128, v126
	v_mov_b32_e32 v129, v126
	s_setprio 1
	s_waitcnt lgkmcnt(7)
	v_mfma_f32_16x16x32_bf16 v[64:67], v[64:67], v[76:79], v[126:129]
	s_waitcnt lgkmcnt(6)
	v_mfma_f32_16x16x32_bf16 v[64:67], v[68:71], v[80:83], v[64:67]
	s_waitcnt lgkmcnt(5)
	v_mfma_f32_16x16x32_bf16 v[68:71], v[72:75], v[76:79], v[126:129]
	s_waitcnt lgkmcnt(4)
	v_mfma_f32_16x16x32_bf16 v[68:71], v[122:125], v[80:83], v[68:71]
	s_waitcnt lgkmcnt(3)
	v_mfma_f32_16x16x32_bf16 v[72:75], v[130:133], v[76:79], v[126:129]
	s_waitcnt lgkmcnt(2)
	v_mfma_f32_16x16x32_bf16 v[72:75], v[134:137], v[80:83], v[72:75]
	s_waitcnt lgkmcnt(1)
	v_mfma_f32_16x16x32_bf16 v[76:79], v[174:177], v[76:79], v[126:129]
	s_waitcnt lgkmcnt(0)
	v_mfma_f32_16x16x32_bf16 v[76:79], v[138:141], v[80:83], v[76:79]
	s_setprio 0
	s_and_b64 vcc, exec, s[72:73]
	s_cbranch_vccnz .LBB0_1067
	v_add_u32_e32 v80, v120, v111
	v_cmp_lt_i32_e32 vcc, -1, v80
	s_nop 1
	v_cndmask_b32_e32 v64, v222, v64, vcc
	v_cmp_lt_i32_e32 vcc, 0, v80
	s_nop 1
	v_cndmask_b32_e32 v65, v222, v65, vcc
	v_cmp_lt_i32_e32 vcc, 1, v80
	s_nop 1
	v_cndmask_b32_e32 v66, v222, v66, vcc
	v_cmp_lt_i32_e32 vcc, 2, v80
	s_nop 1
	v_cndmask_b32_e32 v67, v222, v67, vcc
	v_cmp_lt_i32_e32 vcc, 15, v80
	s_nop 1
	v_cndmask_b32_e32 v68, v222, v68, vcc
	v_cmp_lt_i32_e32 vcc, 16, v80
	s_nop 1
	v_cndmask_b32_e32 v69, v222, v69, vcc
	v_cmp_lt_i32_e32 vcc, 17, v80
	s_nop 1
	v_cndmask_b32_e32 v70, v222, v70, vcc
	v_cmp_lt_i32_e32 vcc, 18, v80
	s_nop 1
	v_cndmask_b32_e32 v71, v222, v71, vcc
	v_cmp_lt_i32_e32 vcc, 31, v80
	s_nop 1
	v_cndmask_b32_e32 v72, v222, v72, vcc
	v_cmp_lt_i32_e32 vcc, 32, v80
	s_nop 1
	v_cndmask_b32_e32 v73, v222, v73, vcc
	v_cmp_lt_i32_e32 vcc, 33, v80
	s_nop 1
	v_cndmask_b32_e32 v74, v222, v74, vcc
	v_cmp_lt_i32_e32 vcc, 34, v80
	s_nop 1
	v_cndmask_b32_e32 v75, v222, v75, vcc
	v_cmp_lt_i32_e32 vcc, 47, v80
	s_nop 1
	v_cndmask_b32_e32 v76, v222, v76, vcc
	v_cmp_lt_i32_e32 vcc, 48, v80
	s_nop 1
	v_cndmask_b32_e32 v77, v222, v77, vcc
	v_cmp_lt_i32_e32 vcc, 49, v80
	s_nop 1
	v_cndmask_b32_e32 v78, v222, v78, vcc
	v_cmp_lt_i32_e32 vcc, 50, v80
	s_nop 1
	v_cndmask_b32_e32 v79, v222, v79, vcc
